# sc1 (write-through) on the 16-byte converted-weight stores so the grid barrier after the conversion has little dirty L2 data to write back
# speedup vs baseline: 1.0116x; 1.0102x over previous
.LBB0_697:
	v_add_u32_e32 v4, 0xc60, v28
	ds_write2_b32 v4, v18, v19 offset1:1
	v_add_u32_e32 v4, 0xc68, v28
	ds_write2_b32 v4, v16, v17 offset1:1
	v_add_u32_e32 v4, 0x1080, v28
	ds_write2_b32 v4, v12, v13 offset1:1
	v_add_u32_e32 v4, 0x1088, v28
	ds_write2_b32 v4, v14, v15 offset1:1
	s_mulk_i32 s52, 0xea00
	s_waitcnt lgkmcnt(0)
	s_add_i32 s6, s47, s52
	s_and_b32 s6, s6, 0xffffff00
	s_and_b32 s7, s26, 0x60
	ds_read2_b32 v[8:9], v90 offset0:33 offset1:41
	ds_read2_b32 v[10:11], v90 offset1:8
	ds_read2_b32 v[12:13], v90 offset0:66 offset1:74
	ds_read2_b32 v[14:15], v90 offset0:99 offset1:107
	ds_read2_b32 v[16:17], v90 offset0:132 offset1:140
	ds_read2_b32 v[18:19], v90 offset0:165 offset1:173
	ds_read2_b32 v[20:21], v90 offset0:198 offset1:206
	ds_read2_b32 v[22:23], v90 offset0:231 offset1:239
	s_or_b32 s6, s6, s7
	v_or_b32_e32 v26, s6, v0
	v_ashrrev_i32_e32 v27, 31, v26
	v_lshl_add_u64 v[24:25], s[18:19], 1, v[56:57]
	v_lshlrev_b64 v[26:27], 11, v[26:27]
	s_waitcnt lgkmcnt(6)
	v_cvt_pk_bf16_f32 v4, v10, v8
	s_waitcnt lgkmcnt(4)
	v_cvt_pk_bf16_f32 v5, v12, v14
	s_waitcnt lgkmcnt(2)
	v_cvt_pk_bf16_f32 v6, v16, v18
	s_waitcnt lgkmcnt(0)
	v_cvt_pk_bf16_f32 v7, v20, v22
	v_lshl_add_u64 v[26:27], v[24:25], 0, v[26:27]
	v_or_b32_e32 v8, s6, v85
	global_store_dwordx4 v[26:27], v[4:7], off sc1
	s_nop 1
	v_cvt_pk_bf16_f32 v4, v11, v9
	v_ashrrev_i32_e32 v9, 31, v8
	v_cvt_pk_bf16_f32 v5, v13, v15
	v_cvt_pk_bf16_f32 v6, v17, v19
	v_cvt_pk_bf16_f32 v7, v21, v23
	v_lshlrev_b64 v[8:9], 11, v[8:9]
	ds_read2_b32 v[10:11], v90 offset0:49 offset1:57
	ds_read2_b32 v[12:13], v90 offset0:16 offset1:24
	ds_read2_b32 v[14:15], v90 offset0:82 offset1:90
	ds_read2_b32 v[16:17], v90 offset0:115 offset1:123
	ds_read2_b32 v[18:19], v90 offset0:148 offset1:156
	ds_read2_b32 v[20:21], v90 offset0:181 offset1:189
	ds_read2_b32 v[22:23], v90 offset0:214 offset1:222
	ds_read2_b32 v[26:27], v90 offset0:247 offset1:255
	v_lshl_add_u64 v[8:9], v[24:25], 0, v[8:9]
	global_store_dwordx4 v[8:9], v[4:7], off sc1
	v_or_b32_e32 v8, s6, v86
	v_ashrrev_i32_e32 v9, 31, v8
	v_lshlrev_b64 v[8:9], 11, v[8:9]
	s_waitcnt lgkmcnt(6)
	v_cvt_pk_bf16_f32 v4, v12, v10
	s_waitcnt lgkmcnt(4)
	v_cvt_pk_bf16_f32 v5, v14, v16
	s_waitcnt lgkmcnt(2)
	v_cvt_pk_bf16_f32 v6, v18, v20
	s_waitcnt lgkmcnt(0)
	v_cvt_pk_bf16_f32 v7, v22, v26
	v_lshl_add_u64 v[8:9], v[24:25], 0, v[8:9]
	global_store_dwordx4 v[8:9], v[4:7], off sc1
	v_or_b32_e32 v8, s6, v88
	v_ashrrev_i32_e32 v9, 31, v8
	v_lshlrev_b64 v[8:9], 11, v[8:9]
	v_cvt_pk_bf16_f32 v4, v13, v11
	v_cvt_pk_bf16_f32 v5, v15, v17
	v_cvt_pk_bf16_f32 v6, v19, v21
	v_cvt_pk_bf16_f32 v7, v23, v27
	v_lshl_add_u64 v[8:9], v[24:25], 0, v[8:9]
	global_store_dwordx4 v[8:9], v[4:7], off sc1
	s_waitcnt lgkmcnt(0)

.LBB0_721:
	v_add_u32_e32 v4, 0xc60, v28
	ds_write2_b32 v4, v18, v19 offset1:1
	v_add_u32_e32 v4, 0xc68, v28
	ds_write2_b32 v4, v16, v17 offset1:1
	v_add_u32_e32 v4, 0x1080, v28
	ds_write2_b32 v4, v12, v13 offset1:1
	v_add_u32_e32 v4, 0x1088, v28
	ds_write2_b32 v4, v14, v15 offset1:1
	s_waitcnt lgkmcnt(0)
	s_and_b32 s6, s49, 0x7ffff800
	s_lshl_b32 s7, s36, 10
	ds_read2_b32 v[8:9], v90 offset0:33 offset1:41
	ds_read2_b32 v[10:11], v90 offset1:8
	ds_read2_b32 v[12:13], v90 offset0:66 offset1:74
	ds_read2_b32 v[14:15], v90 offset0:99 offset1:107
	ds_read2_b32 v[16:17], v90 offset0:132 offset1:140
	ds_read2_b32 v[18:19], v90 offset0:165 offset1:173
	ds_read2_b32 v[20:21], v90 offset0:198 offset1:206
	ds_read2_b32 v[22:23], v90 offset0:231 offset1:239
	s_or_b32 s6, s7, s6
	s_and_b32 s7, 0xffff, s52
	s_or_b32 s6, s6, s7
	s_lshl_b32 s90, s37, 1
	v_or_b32_e32 v180, s6, v0
	v_lshl_add_u64 v[24:25], v[40:41], 0, s[90:91]
	v_lshlrev_b64 v[26:27], 11, v[180:181]
	s_waitcnt lgkmcnt(6)
	v_cvt_pk_bf16_f32 v4, v10, v8
	s_waitcnt lgkmcnt(4)
	v_cvt_pk_bf16_f32 v5, v12, v14
	s_waitcnt lgkmcnt(2)
	v_cvt_pk_bf16_f32 v6, v16, v18
	s_waitcnt lgkmcnt(0)
	v_cvt_pk_bf16_f32 v7, v20, v22
	v_lshl_add_u64 v[26:27], v[24:25], 0, v[26:27]
	global_store_dwordx4 v[26:27], v[4:7], off sc1
	v_or_b32_e32 v180, s6, v85
	s_nop 0
	v_cvt_pk_bf16_f32 v4, v11, v9
	v_cvt_pk_bf16_f32 v5, v13, v15
	v_cvt_pk_bf16_f32 v6, v17, v19
	v_cvt_pk_bf16_f32 v7, v21, v23
	ds_read2_b32 v[10:11], v90 offset0:49 offset1:57
	ds_read2_b32 v[12:13], v90 offset0:16 offset1:24
	ds_read2_b32 v[14:15], v90 offset0:82 offset1:90
	ds_read2_b32 v[16:17], v90 offset0:115 offset1:123
	ds_read2_b32 v[18:19], v90 offset0:148 offset1:156
	ds_read2_b32 v[20:21], v90 offset0:181 offset1:189
	ds_read2_b32 v[22:23], v90 offset0:214 offset1:222
	ds_read2_b32 v[26:27], v90 offset0:247 offset1:255
	v_lshlrev_b64 v[8:9], 11, v[180:181]
	v_lshl_add_u64 v[8:9], v[24:25], 0, v[8:9]
	v_or_b32_e32 v180, s6, v86
	global_store_dwordx4 v[8:9], v[4:7], off sc1
	v_lshlrev_b64 v[8:9], 11, v[180:181]
	v_lshl_add_u64 v[8:9], v[24:25], 0, v[8:9]
	s_waitcnt lgkmcnt(6)
	v_cvt_pk_bf16_f32 v4, v12, v10
	s_waitcnt lgkmcnt(4)
	v_cvt_pk_bf16_f32 v5, v14, v16
	s_waitcnt lgkmcnt(2)
	v_cvt_pk_bf16_f32 v6, v18, v20
	s_waitcnt lgkmcnt(0)
	v_cvt_pk_bf16_f32 v7, v22, v26
	v_or_b32_e32 v180, s6, v88
	global_store_dwordx4 v[8:9], v[4:7], off sc1
	v_lshlrev_b64 v[8:9], 11, v[180:181]
	v_lshl_add_u64 v[8:9], v[24:25], 0, v[8:9]
	v_cvt_pk_bf16_f32 v4, v13, v11
	v_cvt_pk_bf16_f32 v5, v15, v17
	v_cvt_pk_bf16_f32 v6, v19, v21
	v_cvt_pk_bf16_f32 v7, v23, v27
	global_store_dwordx4 v[8:9], v[4:7], off sc1
	s_waitcnt lgkmcnt(0)
	s_mov_b64 s[6:7], 0
.LBB0_722:
	s_and_b64 vcc, exec, s[6:7]
	s_cbranch_vccz .LBB0_724
	s_add_i32 s6, s49, 0x20400
	s_and_b32 s7, s6, 0x1ffc0
	s_lshl_b32 s6, s51, 5
	s_and_b32 s6, s6, 0x3e0
	v_or_b32_e32 v6, s7, v0
	s_lshl_b32 s90, s6, 2
	v_lshl_add_u64 v[4:5], v[58:59], 0, s[90:91]
	v_lshlrev_b32_e32 v180, 12, v6
	v_lshl_add_u64 v[32:33], v[4:5], 0, v[180:181]
	v_add_co_u32_e32 v8, vcc, 0x8000, v32
	global_load_dwordx4 v[4:7], v[32:33], off nt
	s_nop 0
	v_addc_co_u32_e32 v9, vcc, 0, v33, vcc
	s_mov_b32 s0, 0x10000
	global_load_dwordx4 v[8:11], v[8:9], off nt
	v_add_co_u32_e32 v12, vcc, s0, v32
	s_mov_b32 s0, 0x18000
	s_nop 0
	v_addc_co_u32_e32 v13, vcc, 0, v33, vcc
	global_load_dwordx4 v[12:15], v[12:13], off nt
	s_waitcnt vmcnt(0)
	v_add_co_u32_e32 v16, vcc, s0, v32
	v_add_u32_e32 v36, v3, v84
	s_nop 0
	v_addc_co_u32_e32 v17, vcc, 0, v33, vcc
	global_load_dwordx4 v[16:19], v[16:17], off nt
	v_add_co_u32_e32 v20, vcc, 0x20000, v32
	s_lshl_b32 s90, s7, 1
	s_nop 0
	v_addc_co_u32_e32 v21, vcc, 0, v33, vcc
	global_load_dwordx4 v[20:23], v[20:21], off nt
	v_add_co_u32_e32 v24, vcc, 0x28000, v32
	s_nop 1
	v_addc_co_u32_e32 v25, vcc, 0, v33, vcc
	global_load_dwordx4 v[24:27], v[24:25], off nt
	v_add_co_u32_e32 v28, vcc, 0x30000, v32
	s_nop 1
	v_addc_co_u32_e32 v29, vcc, 0, v33, vcc
	global_load_dwordx4 v[28:31], v[28:29], off nt
	v_add_co_u32_e32 v32, vcc, 0x38000, v32
	s_nop 1
	v_addc_co_u32_e32 v33, vcc, 0, v33, vcc
	global_load_dwordx4 v[32:35], v[32:33], off nt
	ds_write2_b32 v36, v4, v5 offset1:1
	ds_write2_b32 v36, v6, v7 offset0:2 offset1:3
	v_add_u32_e32 v4, 0x420, v36
	ds_write2_b32 v4, v8, v9 offset1:1
	v_add_u32_e32 v4, 0x428, v36
	ds_write2_b32 v4, v10, v11 offset1:1
	v_add_u32_e32 v4, 0x840, v36
	ds_write2_b32 v4, v12, v13 offset1:1
	v_add_u32_e32 v4, 0x848, v36
	ds_write2_b32 v4, v14, v15 offset1:1
	v_add_u32_e32 v4, 0xc60, v36
	s_waitcnt vmcnt(4)
	ds_write2_b32 v4, v16, v17 offset1:1
	v_add_u32_e32 v4, 0xc68, v36
	ds_write2_b32 v4, v18, v19 offset1:1
	v_add_u32_e32 v4, 0x1080, v36
	s_waitcnt vmcnt(3)
	ds_write2_b32 v4, v20, v21 offset1:1
	v_add_u32_e32 v4, 0x1088, v36
	ds_write2_b32 v4, v22, v23 offset1:1
	v_add_u32_e32 v4, 0x14a0, v36
	s_waitcnt vmcnt(2)
	ds_write2_b32 v4, v24, v25 offset1:1
	v_add_u32_e32 v4, 0x14a8, v36
	ds_write2_b32 v4, v26, v27 offset1:1
	v_add_u32_e32 v4, 0x18c0, v36
	s_waitcnt vmcnt(1)
	ds_write2_b32 v4, v28, v29 offset1:1
	v_add_u32_e32 v4, 0x18c8, v36
	ds_write2_b32 v4, v30, v31 offset1:1
	v_add_u32_e32 v4, 0x1ce0, v36
	s_waitcnt vmcnt(0)
	ds_write2_b32 v4, v32, v33 offset1:1
	v_add_u32_e32 v4, 0x1ce8, v36
	ds_write2_b32 v4, v34, v35 offset1:1
	s_waitcnt lgkmcnt(0)
	ds_read2_b32 v[10:11], v90 offset0:33 offset1:41
	ds_read2_b32 v[12:13], v90 offset1:8
	ds_read2_b32 v[14:15], v90 offset0:66 offset1:74
	ds_read2_b32 v[16:17], v90 offset0:99 offset1:107
	ds_read2_b32 v[18:19], v90 offset0:132 offset1:140
	ds_read2_b32 v[20:21], v90 offset0:165 offset1:173
	ds_read2_b32 v[22:23], v90 offset0:198 offset1:206
	ds_read2_b32 v[24:25], v90 offset0:231 offset1:239
	v_lshl_add_u64 v[4:5], v[42:43], 0, s[90:91]
	s_waitcnt lgkmcnt(6)
	v_cvt_pk_bf16_f32 v6, v12, v10
	v_or_b32_e32 v10, s6, v0
	v_lshlrev_b32_e32 v180, 11, v10
	v_or_b32_e32 v10, s6, v85
	s_waitcnt lgkmcnt(4)
	v_cvt_pk_bf16_f32 v7, v14, v16
	s_waitcnt lgkmcnt(2)
	v_cvt_pk_bf16_f32 v8, v18, v20
	s_waitcnt lgkmcnt(0)
	v_cvt_pk_bf16_f32 v9, v22, v24
	v_lshl_add_u64 v[26:27], v[4:5], 0, v[180:181]
	v_lshlrev_b32_e32 v180, 11, v10
	global_store_dwordx4 v[26:27], v[6:9], off sc1
	s_nop 1
	v_cvt_pk_bf16_f32 v6, v13, v11
	v_cvt_pk_bf16_f32 v7, v15, v17
	v_cvt_pk_bf16_f32 v8, v19, v21
	v_cvt_pk_bf16_f32 v9, v23, v25
	v_lshl_add_u64 v[10:11], v[4:5], 0, v[180:181]
	global_store_dwordx4 v[10:11], v[6:9], off sc1
	ds_read2_b32 v[10:11], v90 offset0:49 offset1:57
	ds_read2_b32 v[12:13], v90 offset0:16 offset1:24
	ds_read2_b32 v[14:15], v90 offset0:82 offset1:90
	ds_read2_b32 v[16:17], v90 offset0:115 offset1:123
	ds_read2_b32 v[18:19], v90 offset0:148 offset1:156
	ds_read2_b32 v[20:21], v90 offset0:181 offset1:189
	ds_read2_b32 v[22:23], v90 offset0:214 offset1:222
	ds_read2_b32 v[24:25], v90 offset0:247 offset1:255
	s_waitcnt lgkmcnt(6)
	v_cvt_pk_bf16_f32 v6, v12, v10
	v_or_b32_e32 v10, s6, v86
	v_lshlrev_b32_e32 v180, 11, v10
	v_or_b32_e32 v10, s6, v88
	s_waitcnt lgkmcnt(4)
	v_cvt_pk_bf16_f32 v7, v14, v16
	s_waitcnt lgkmcnt(2)
	v_cvt_pk_bf16_f32 v8, v18, v20
	s_waitcnt lgkmcnt(0)
	v_cvt_pk_bf16_f32 v9, v22, v24
	v_lshl_add_u64 v[26:27], v[4:5], 0, v[180:181]
	v_lshlrev_b32_e32 v180, 11, v10
	global_store_dwordx4 v[26:27], v[6:9], off sc1
	v_lshl_add_u64 v[4:5], v[4:5], 0, v[180:181]
	s_nop 0
	v_cvt_pk_bf16_f32 v6, v13, v11
	v_cvt_pk_bf16_f32 v7, v15, v17
	v_cvt_pk_bf16_f32 v8, v19, v21
	v_cvt_pk_bf16_f32 v9, v23, v25
	global_store_dwordx4 v[4:5], v[6:9], off sc1
	s_waitcnt lgkmcnt(0)

.LBB0_738:
	v_add_u32_e32 v4, 0xc60, v28
	ds_write2_b32 v4, v18, v19 offset1:1
	v_add_u32_e32 v4, 0xc68, v28
	ds_write2_b32 v4, v16, v17 offset1:1
	v_add_u32_e32 v4, 0x1080, v28
	ds_write2_b32 v4, v12, v13 offset1:1
	v_add_u32_e32 v4, 0x1088, v28
	ds_write2_b32 v4, v14, v15 offset1:1
	s_waitcnt lgkmcnt(0)
	ds_read2_b32 v[8:9], v90 offset0:33 offset1:41
	ds_read2_b32 v[10:11], v90 offset1:8
	ds_read2_b32 v[12:13], v90 offset0:66 offset1:74
	ds_read2_b32 v[14:15], v90 offset0:99 offset1:107
	ds_read2_b32 v[16:17], v90 offset0:132 offset1:140
	ds_read2_b32 v[18:19], v90 offset0:165 offset1:173
	ds_read2_b32 v[20:21], v90 offset0:198 offset1:206
	ds_read2_b32 v[22:23], v90 offset0:231 offset1:239
	s_and_b32 s6, 0xffff, s27
	s_lshl_b32 s90, s26, 1
	s_waitcnt lgkmcnt(6)
	v_cvt_pk_bf16_f32 v4, v10, v8
	v_or_b32_e32 v8, s6, v0
	v_lshl_add_u64 v[24:25], v[44:45], 0, s[90:91]
	v_lshlrev_b32_e32 v180, 11, v8
	s_waitcnt lgkmcnt(4)
	v_cvt_pk_bf16_f32 v5, v12, v14
	s_waitcnt lgkmcnt(2)
	v_cvt_pk_bf16_f32 v6, v16, v18
	s_waitcnt lgkmcnt(0)
	v_cvt_pk_bf16_f32 v7, v20, v22
	v_lshl_add_u64 v[26:27], v[24:25], 0, v[180:181]
	global_store_dwordx4 v[26:27], v[4:7], off sc1
	v_or_b32_e32 v8, s6, v85
	v_lshlrev_b32_e32 v180, 11, v8
	v_cvt_pk_bf16_f32 v4, v11, v9
	v_cvt_pk_bf16_f32 v5, v13, v15
	v_cvt_pk_bf16_f32 v6, v17, v19
	v_cvt_pk_bf16_f32 v7, v21, v23
	ds_read2_b32 v[10:11], v90 offset0:49 offset1:57
	ds_read2_b32 v[12:13], v90 offset0:16 offset1:24
	ds_read2_b32 v[14:15], v90 offset0:82 offset1:90
	ds_read2_b32 v[16:17], v90 offset0:115 offset1:123
	ds_read2_b32 v[18:19], v90 offset0:148 offset1:156
	ds_read2_b32 v[20:21], v90 offset0:181 offset1:189
	ds_read2_b32 v[22:23], v90 offset0:214 offset1:222
	ds_read2_b32 v[26:27], v90 offset0:247 offset1:255
	v_lshl_add_u64 v[8:9], v[24:25], 0, v[180:181]
	global_store_dwordx4 v[8:9], v[4:7], off sc1
	v_or_b32_e32 v8, s6, v86
	v_lshlrev_b32_e32 v180, 11, v8
	s_waitcnt lgkmcnt(6)
	v_cvt_pk_bf16_f32 v4, v12, v10
	s_waitcnt lgkmcnt(4)
	v_cvt_pk_bf16_f32 v5, v14, v16
	s_waitcnt lgkmcnt(2)
	v_cvt_pk_bf16_f32 v6, v18, v20
	s_waitcnt lgkmcnt(0)
	v_cvt_pk_bf16_f32 v7, v22, v26
	v_lshl_add_u64 v[8:9], v[24:25], 0, v[180:181]
	global_store_dwordx4 v[8:9], v[4:7], off sc1
	v_or_b32_e32 v8, s6, v88
	v_lshlrev_b32_e32 v180, 11, v8
	v_cvt_pk_bf16_f32 v4, v13, v11
	v_cvt_pk_bf16_f32 v5, v15, v17
	v_cvt_pk_bf16_f32 v6, v19, v21
	v_cvt_pk_bf16_f32 v7, v23, v27
	v_lshl_add_u64 v[8:9], v[24:25], 0, v[180:181]
	global_store_dwordx4 v[8:9], v[4:7], off sc1
	s_waitcnt lgkmcnt(0)

.LBB0_740:
	s_andn2_b64 vcc, exec, s[6:7]
	s_cbranch_vccnz .LBB0_742
	s_add_i32 s6, s49, 0x20c00
	s_and_b32 s7, s6, 0x1ffc0
	s_lshl_b32 s6, s51, 5
	s_and_b32 s6, s6, 0x3e0
	v_or_b32_e32 v6, s7, v0
	s_lshl_b32 s90, s6, 2
	v_lshl_add_u64 v[4:5], v[62:63], 0, s[90:91]
	v_lshlrev_b32_e32 v180, 12, v6
	v_lshl_add_u64 v[32:33], v[4:5], 0, v[180:181]
	v_add_co_u32_e32 v8, vcc, 0x8000, v32
	global_load_dwordx4 v[4:7], v[32:33], off nt
	s_nop 0
	v_addc_co_u32_e32 v9, vcc, 0, v33, vcc
	s_mov_b32 s0, 0x10000
	global_load_dwordx4 v[8:11], v[8:9], off nt
	v_add_co_u32_e32 v12, vcc, s0, v32
	s_mov_b32 s0, 0x18000
	s_nop 0
	v_addc_co_u32_e32 v13, vcc, 0, v33, vcc
	global_load_dwordx4 v[12:15], v[12:13], off nt
	s_waitcnt vmcnt(0)
	v_add_co_u32_e32 v16, vcc, s0, v32
	v_add_u32_e32 v36, v3, v84
	s_nop 0
	v_addc_co_u32_e32 v17, vcc, 0, v33, vcc
	global_load_dwordx4 v[16:19], v[16:17], off nt
	v_add_co_u32_e32 v20, vcc, 0x20000, v32
	s_lshl_b32 s90, s7, 1
	s_nop 0
	v_addc_co_u32_e32 v21, vcc, 0, v33, vcc
	global_load_dwordx4 v[20:23], v[20:21], off nt
	v_add_co_u32_e32 v24, vcc, 0x28000, v32
	s_nop 1
	v_addc_co_u32_e32 v25, vcc, 0, v33, vcc
	global_load_dwordx4 v[24:27], v[24:25], off nt
	v_add_co_u32_e32 v28, vcc, 0x30000, v32
	s_nop 1
	v_addc_co_u32_e32 v29, vcc, 0, v33, vcc
	global_load_dwordx4 v[28:31], v[28:29], off nt
	v_add_co_u32_e32 v32, vcc, 0x38000, v32
	s_nop 1
	v_addc_co_u32_e32 v33, vcc, 0, v33, vcc
	global_load_dwordx4 v[32:35], v[32:33], off nt
	ds_write2_b32 v36, v4, v5 offset1:1
	ds_write2_b32 v36, v6, v7 offset0:2 offset1:3
	v_add_u32_e32 v4, 0x420, v36
	ds_write2_b32 v4, v8, v9 offset1:1
	v_add_u32_e32 v4, 0x428, v36
	ds_write2_b32 v4, v10, v11 offset1:1
	v_add_u32_e32 v4, 0x840, v36
	ds_write2_b32 v4, v12, v13 offset1:1
	v_add_u32_e32 v4, 0x848, v36
	ds_write2_b32 v4, v14, v15 offset1:1
	v_add_u32_e32 v4, 0xc60, v36
	s_waitcnt vmcnt(4)
	ds_write2_b32 v4, v16, v17 offset1:1
	v_add_u32_e32 v4, 0xc68, v36
	ds_write2_b32 v4, v18, v19 offset1:1
	v_add_u32_e32 v4, 0x1080, v36
	s_waitcnt vmcnt(3)
	ds_write2_b32 v4, v20, v21 offset1:1
	v_add_u32_e32 v4, 0x1088, v36
	ds_write2_b32 v4, v22, v23 offset1:1
	v_add_u32_e32 v4, 0x14a0, v36
	s_waitcnt vmcnt(2)
	ds_write2_b32 v4, v24, v25 offset1:1
	v_add_u32_e32 v4, 0x14a8, v36
	ds_write2_b32 v4, v26, v27 offset1:1
	v_add_u32_e32 v4, 0x18c0, v36
	s_waitcnt vmcnt(1)
	ds_write2_b32 v4, v28, v29 offset1:1
	v_add_u32_e32 v4, 0x18c8, v36
	ds_write2_b32 v4, v30, v31 offset1:1
	v_add_u32_e32 v4, 0x1ce0, v36
	s_waitcnt vmcnt(0)
	ds_write2_b32 v4, v32, v33 offset1:1
	v_add_u32_e32 v4, 0x1ce8, v36
	ds_write2_b32 v4, v34, v35 offset1:1
	s_waitcnt lgkmcnt(0)
	ds_read2_b32 v[10:11], v90 offset0:33 offset1:41
	ds_read2_b32 v[12:13], v90 offset1:8
	ds_read2_b32 v[14:15], v90 offset0:66 offset1:74
	ds_read2_b32 v[16:17], v90 offset0:99 offset1:107
	ds_read2_b32 v[18:19], v90 offset0:132 offset1:140
	ds_read2_b32 v[20:21], v90 offset0:165 offset1:173
	ds_read2_b32 v[22:23], v90 offset0:198 offset1:206
	ds_read2_b32 v[24:25], v90 offset0:231 offset1:239
	v_lshl_add_u64 v[4:5], v[46:47], 0, s[90:91]
	s_waitcnt lgkmcnt(6)
	v_cvt_pk_bf16_f32 v6, v12, v10
	v_or_b32_e32 v10, s6, v0
	v_lshlrev_b32_e32 v180, 11, v10
	v_or_b32_e32 v10, s6, v85
	s_waitcnt lgkmcnt(4)
	v_cvt_pk_bf16_f32 v7, v14, v16
	s_waitcnt lgkmcnt(2)
	v_cvt_pk_bf16_f32 v8, v18, v20
	s_waitcnt lgkmcnt(0)
	v_cvt_pk_bf16_f32 v9, v22, v24
	v_lshl_add_u64 v[26:27], v[4:5], 0, v[180:181]
	v_lshlrev_b32_e32 v180, 11, v10
	global_store_dwordx4 v[26:27], v[6:9], off sc1
	s_nop 1
	v_cvt_pk_bf16_f32 v6, v13, v11
	v_cvt_pk_bf16_f32 v7, v15, v17
	v_cvt_pk_bf16_f32 v8, v19, v21
	v_cvt_pk_bf16_f32 v9, v23, v25
	v_lshl_add_u64 v[10:11], v[4:5], 0, v[180:181]
	global_store_dwordx4 v[10:11], v[6:9], off sc1
	ds_read2_b32 v[10:11], v90 offset0:49 offset1:57
	ds_read2_b32 v[12:13], v90 offset0:16 offset1:24
	ds_read2_b32 v[14:15], v90 offset0:82 offset1:90
	ds_read2_b32 v[16:17], v90 offset0:115 offset1:123
	ds_read2_b32 v[18:19], v90 offset0:148 offset1:156
	ds_read2_b32 v[20:21], v90 offset0:181 offset1:189
	ds_read2_b32 v[22:23], v90 offset0:214 offset1:222
	ds_read2_b32 v[24:25], v90 offset0:247 offset1:255
	s_waitcnt lgkmcnt(6)
	v_cvt_pk_bf16_f32 v6, v12, v10
	v_or_b32_e32 v10, s6, v86
	v_lshlrev_b32_e32 v180, 11, v10
	v_or_b32_e32 v10, s6, v88
	s_waitcnt lgkmcnt(4)
	v_cvt_pk_bf16_f32 v7, v14, v16
	s_waitcnt lgkmcnt(2)
	v_cvt_pk_bf16_f32 v8, v18, v20
	s_waitcnt lgkmcnt(0)
	v_cvt_pk_bf16_f32 v9, v22, v24
	v_lshl_add_u64 v[26:27], v[4:5], 0, v[180:181]
	v_lshlrev_b32_e32 v180, 11, v10
	global_store_dwordx4 v[26:27], v[6:9], off sc1
	v_lshl_add_u64 v[4:5], v[4:5], 0, v[180:181]
	s_nop 0
	v_cvt_pk_bf16_f32 v6, v13, v11
	v_cvt_pk_bf16_f32 v7, v15, v17
	v_cvt_pk_bf16_f32 v8, v19, v21
	v_cvt_pk_bf16_f32 v9, v23, v25
	global_store_dwordx4 v[4:5], v[6:9], off sc1
	s_waitcnt lgkmcnt(0)

.LBB0_756:
	v_add_u32_e32 v4, 0xc60, v28
	ds_write2_b32 v4, v18, v19 offset1:1
	v_add_u32_e32 v4, 0xc68, v28
	ds_write2_b32 v4, v16, v17 offset1:1
	v_add_u32_e32 v4, 0x1080, v28
	ds_write2_b32 v4, v12, v13 offset1:1
	v_add_u32_e32 v4, 0x1088, v28
	ds_write2_b32 v4, v14, v15 offset1:1
	s_waitcnt lgkmcnt(0)
	ds_read2_b32 v[8:9], v90 offset0:33 offset1:41
	ds_read2_b32 v[10:11], v90 offset1:8
	ds_read2_b32 v[12:13], v90 offset0:66 offset1:74
	ds_read2_b32 v[14:15], v90 offset0:99 offset1:107
	ds_read2_b32 v[16:17], v90 offset0:132 offset1:140
	ds_read2_b32 v[18:19], v90 offset0:165 offset1:173
	ds_read2_b32 v[20:21], v90 offset0:198 offset1:206
	ds_read2_b32 v[22:23], v90 offset0:231 offset1:239
	s_lshl_b32 s6, s27, 5
	s_and_b32 s6, 0xffff, s6
	s_lshl_b32 s90, s26, 1
	s_waitcnt lgkmcnt(6)
	v_cvt_pk_bf16_f32 v4, v10, v8
	v_or_b32_e32 v8, s6, v0
	v_lshl_add_u64 v[24:25], v[48:49], 0, s[90:91]
	v_lshlrev_b32_e32 v180, 11, v8
	s_waitcnt lgkmcnt(4)
	v_cvt_pk_bf16_f32 v5, v12, v14
	s_waitcnt lgkmcnt(2)
	v_cvt_pk_bf16_f32 v6, v16, v18
	s_waitcnt lgkmcnt(0)
	v_cvt_pk_bf16_f32 v7, v20, v22
	v_lshl_add_u64 v[26:27], v[24:25], 0, v[180:181]
	global_store_dwordx4 v[26:27], v[4:7], off sc1
	v_or_b32_e32 v8, s6, v85
	v_lshlrev_b32_e32 v180, 11, v8
	v_cvt_pk_bf16_f32 v4, v11, v9
	v_cvt_pk_bf16_f32 v5, v13, v15
	v_cvt_pk_bf16_f32 v6, v17, v19
	v_cvt_pk_bf16_f32 v7, v21, v23
	ds_read2_b32 v[10:11], v90 offset0:49 offset1:57
	ds_read2_b32 v[12:13], v90 offset0:16 offset1:24
	ds_read2_b32 v[14:15], v90 offset0:82 offset1:90
	ds_read2_b32 v[16:17], v90 offset0:115 offset1:123
	ds_read2_b32 v[18:19], v90 offset0:148 offset1:156
	ds_read2_b32 v[20:21], v90 offset0:181 offset1:189
	ds_read2_b32 v[22:23], v90 offset0:214 offset1:222
	ds_read2_b32 v[26:27], v90 offset0:247 offset1:255
	v_lshl_add_u64 v[8:9], v[24:25], 0, v[180:181]
	global_store_dwordx4 v[8:9], v[4:7], off sc1
	v_or_b32_e32 v8, s6, v86
	v_lshlrev_b32_e32 v180, 11, v8
	s_waitcnt lgkmcnt(6)
	v_cvt_pk_bf16_f32 v4, v12, v10
	s_waitcnt lgkmcnt(4)
	v_cvt_pk_bf16_f32 v5, v14, v16
	s_waitcnt lgkmcnt(2)
	v_cvt_pk_bf16_f32 v6, v18, v20
	s_waitcnt lgkmcnt(0)
	v_cvt_pk_bf16_f32 v7, v22, v26
	v_lshl_add_u64 v[8:9], v[24:25], 0, v[180:181]
	global_store_dwordx4 v[8:9], v[4:7], off sc1
	v_or_b32_e32 v8, s6, v88
	v_lshlrev_b32_e32 v180, 11, v8
	v_cvt_pk_bf16_f32 v4, v13, v11
	v_cvt_pk_bf16_f32 v5, v15, v17
	v_cvt_pk_bf16_f32 v6, v19, v21
	v_cvt_pk_bf16_f32 v7, v23, v27
	v_lshl_add_u64 v[8:9], v[24:25], 0, v[180:181]
	global_store_dwordx4 v[8:9], v[4:7], off sc1
	s_waitcnt lgkmcnt(0)

.LBB0_758:
	s_andn2_b64 vcc, exec, s[6:7]
	s_cbranch_vccnz .LBB0_760
	s_add_i32 s6, s49, 0x22500
	s_and_b32 s7, s6, 0x1ffc0
	s_lshl_b32 s6, s51, 5
	s_and_b32 s6, s6, 0x3e0
	v_or_b32_e32 v6, s7, v0
	s_lshl_b32 s90, s6, 2
	v_lshl_add_u64 v[4:5], v[66:67], 0, s[90:91]
	v_lshlrev_b32_e32 v180, 12, v6
	v_lshl_add_u64 v[32:33], v[4:5], 0, v[180:181]
	v_add_co_u32_e32 v8, vcc, 0x8000, v32
	global_load_dwordx4 v[4:7], v[32:33], off nt
	s_nop 0
	v_addc_co_u32_e32 v9, vcc, 0, v33, vcc
	s_mov_b32 s0, 0x10000
	global_load_dwordx4 v[8:11], v[8:9], off nt
	v_add_co_u32_e32 v12, vcc, s0, v32
	s_mov_b32 s0, 0x18000
	s_nop 0
	v_addc_co_u32_e32 v13, vcc, 0, v33, vcc
	global_load_dwordx4 v[12:15], v[12:13], off nt
	s_waitcnt vmcnt(0)
	v_add_co_u32_e32 v16, vcc, s0, v32
	v_add_u32_e32 v36, v3, v84
	s_nop 0
	v_addc_co_u32_e32 v17, vcc, 0, v33, vcc
	global_load_dwordx4 v[16:19], v[16:17], off nt
	v_add_co_u32_e32 v20, vcc, 0x20000, v32
	s_lshl_b32 s90, s7, 1
	s_nop 0
	v_addc_co_u32_e32 v21, vcc, 0, v33, vcc
	global_load_dwordx4 v[20:23], v[20:21], off nt
	v_add_co_u32_e32 v24, vcc, 0x28000, v32
	s_nop 1
	v_addc_co_u32_e32 v25, vcc, 0, v33, vcc
	global_load_dwordx4 v[24:27], v[24:25], off nt
	v_add_co_u32_e32 v28, vcc, 0x30000, v32
	s_nop 1
	v_addc_co_u32_e32 v29, vcc, 0, v33, vcc
	global_load_dwordx4 v[28:31], v[28:29], off nt
	v_add_co_u32_e32 v32, vcc, 0x38000, v32
	s_nop 1
	v_addc_co_u32_e32 v33, vcc, 0, v33, vcc
	global_load_dwordx4 v[32:35], v[32:33], off nt
	ds_write2_b32 v36, v4, v5 offset1:1
	ds_write2_b32 v36, v6, v7 offset0:2 offset1:3
	v_add_u32_e32 v4, 0x420, v36
	ds_write2_b32 v4, v8, v9 offset1:1
	v_add_u32_e32 v4, 0x428, v36
	ds_write2_b32 v4, v10, v11 offset1:1
	v_add_u32_e32 v4, 0x840, v36
	ds_write2_b32 v4, v12, v13 offset1:1
	v_add_u32_e32 v4, 0x848, v36
	ds_write2_b32 v4, v14, v15 offset1:1
	v_add_u32_e32 v4, 0xc60, v36
	s_waitcnt vmcnt(4)
	ds_write2_b32 v4, v16, v17 offset1:1
	v_add_u32_e32 v4, 0xc68, v36
	ds_write2_b32 v4, v18, v19 offset1:1
	v_add_u32_e32 v4, 0x1080, v36
	s_waitcnt vmcnt(3)
	ds_write2_b32 v4, v20, v21 offset1:1
	v_add_u32_e32 v4, 0x1088, v36
	ds_write2_b32 v4, v22, v23 offset1:1
	v_add_u32_e32 v4, 0x14a0, v36
	s_waitcnt vmcnt(2)
	ds_write2_b32 v4, v24, v25 offset1:1
	v_add_u32_e32 v4, 0x14a8, v36
	ds_write2_b32 v4, v26, v27 offset1:1
	v_add_u32_e32 v4, 0x18c0, v36
	s_waitcnt vmcnt(1)
	ds_write2_b32 v4, v28, v29 offset1:1
	v_add_u32_e32 v4, 0x18c8, v36
	ds_write2_b32 v4, v30, v31 offset1:1
	v_add_u32_e32 v4, 0x1ce0, v36
	s_waitcnt vmcnt(0)
	ds_write2_b32 v4, v32, v33 offset1:1
	v_add_u32_e32 v4, 0x1ce8, v36
	ds_write2_b32 v4, v34, v35 offset1:1
	s_waitcnt lgkmcnt(0)
	ds_read2_b32 v[10:11], v90 offset0:33 offset1:41
	ds_read2_b32 v[12:13], v90 offset1:8
	ds_read2_b32 v[14:15], v90 offset0:66 offset1:74
	ds_read2_b32 v[16:17], v90 offset0:99 offset1:107
	ds_read2_b32 v[18:19], v90 offset0:132 offset1:140
	ds_read2_b32 v[20:21], v90 offset0:165 offset1:173
	ds_read2_b32 v[22:23], v90 offset0:198 offset1:206
	ds_read2_b32 v[24:25], v90 offset0:231 offset1:239
	v_lshl_add_u64 v[4:5], v[50:51], 0, s[90:91]
	s_waitcnt lgkmcnt(6)
	v_cvt_pk_bf16_f32 v6, v12, v10
	v_or_b32_e32 v10, s6, v0
	v_mul_u32_u24_e32 v180, 0x1600, v10
	v_or_b32_e32 v10, s6, v85
	s_waitcnt lgkmcnt(4)
	v_cvt_pk_bf16_f32 v7, v14, v16
	s_waitcnt lgkmcnt(2)
	v_cvt_pk_bf16_f32 v8, v18, v20
	s_waitcnt lgkmcnt(0)
	v_cvt_pk_bf16_f32 v9, v22, v24
	v_lshl_add_u64 v[26:27], v[4:5], 0, v[180:181]
	v_mul_u32_u24_e32 v180, 0x1600, v10
	global_store_dwordx4 v[26:27], v[6:9], off sc1
	s_nop 1
	v_cvt_pk_bf16_f32 v6, v13, v11
	v_cvt_pk_bf16_f32 v7, v15, v17
	v_cvt_pk_bf16_f32 v8, v19, v21
	v_cvt_pk_bf16_f32 v9, v23, v25
	v_lshl_add_u64 v[10:11], v[4:5], 0, v[180:181]
	global_store_dwordx4 v[10:11], v[6:9], off sc1
	ds_read2_b32 v[10:11], v90 offset0:16 offset1:24
	ds_read2_b32 v[12:13], v90 offset0:49 offset1:57
	ds_read2_b32 v[14:15], v90 offset0:82 offset1:90
	ds_read2_b32 v[16:17], v90 offset0:115 offset1:123
	ds_read2_b32 v[18:19], v90 offset0:148 offset1:156
	ds_read2_b32 v[20:21], v90 offset0:181 offset1:189
	ds_read2_b32 v[22:23], v90 offset0:214 offset1:222
	ds_read2_b32 v[24:25], v90 offset0:247 offset1:255
	s_waitcnt lgkmcnt(6)
	v_cvt_pk_bf16_f32 v6, v10, v12
	v_or_b32_e32 v10, s6, v86
	v_mul_u32_u24_e32 v180, 0x1600, v10
	v_or_b32_e32 v10, s6, v88
	s_waitcnt lgkmcnt(4)
	v_cvt_pk_bf16_f32 v7, v14, v16
	s_waitcnt lgkmcnt(2)
	v_cvt_pk_bf16_f32 v8, v18, v20
	s_waitcnt lgkmcnt(0)
	v_cvt_pk_bf16_f32 v9, v22, v24
	v_lshl_add_u64 v[26:27], v[4:5], 0, v[180:181]
	v_mul_u32_u24_e32 v180, 0x1600, v10
	global_store_dwordx4 v[26:27], v[6:9], off sc1
	v_lshl_add_u64 v[4:5], v[4:5], 0, v[180:181]
	s_nop 0
	v_cvt_pk_bf16_f32 v6, v11, v13
	v_cvt_pk_bf16_f32 v7, v15, v17
	v_cvt_pk_bf16_f32 v8, v19, v21
	v_cvt_pk_bf16_f32 v9, v23, v25
	global_store_dwordx4 v[4:5], v[6:9], off sc1
	s_waitcnt lgkmcnt(0)

.LBB0_774:
	v_add_u32_e32 v4, 0xc60, v28
	ds_write2_b32 v4, v18, v19 offset1:1
	v_add_u32_e32 v4, 0xc68, v28
	ds_write2_b32 v4, v16, v17 offset1:1
	v_add_u32_e32 v4, 0x1080, v28
	ds_write2_b32 v4, v12, v13 offset1:1
	v_add_u32_e32 v4, 0x1088, v28
	ds_write2_b32 v4, v14, v15 offset1:1
	s_waitcnt lgkmcnt(0)
	s_lshl_b32 s6, s27, 5
	s_lshl_b32 s7, s27, 6
	s_and_b32 s7, s7, 0x1f00
	s_and_b32 s6, s6, 0x60
	ds_read2_b32 v[8:9], v90 offset0:33 offset1:41
	ds_read2_b32 v[10:11], v90 offset1:8
	ds_read2_b32 v[12:13], v90 offset0:66 offset1:74
	ds_read2_b32 v[14:15], v90 offset0:99 offset1:107
	ds_read2_b32 v[16:17], v90 offset0:132 offset1:140
	ds_read2_b32 v[18:19], v90 offset0:165 offset1:173
	ds_read2_b32 v[20:21], v90 offset0:198 offset1:206
	ds_read2_b32 v[22:23], v90 offset0:231 offset1:239
	s_or_b32 s6, s7, s6
	s_bitset1_b32 s6, 7
	s_lshl_b32 s90, s26, 1
	s_waitcnt lgkmcnt(6)
	v_cvt_pk_bf16_f32 v4, v10, v8
	v_or_b32_e32 v8, s6, v0
	v_lshl_add_u64 v[24:25], v[52:53], 0, s[90:91]
	v_lshlrev_b32_e32 v180, 11, v8
	s_waitcnt lgkmcnt(4)
	v_cvt_pk_bf16_f32 v5, v12, v14
	s_waitcnt lgkmcnt(2)
	v_cvt_pk_bf16_f32 v6, v16, v18
	s_waitcnt lgkmcnt(0)
	v_cvt_pk_bf16_f32 v7, v20, v22
	v_lshl_add_u64 v[26:27], v[24:25], 0, v[180:181]
	global_store_dwordx4 v[26:27], v[4:7], off sc1
	v_or_b32_e32 v8, s6, v85
	v_lshlrev_b32_e32 v180, 11, v8
	v_cvt_pk_bf16_f32 v4, v11, v9
	v_cvt_pk_bf16_f32 v5, v13, v15
	v_cvt_pk_bf16_f32 v6, v17, v19
	v_cvt_pk_bf16_f32 v7, v21, v23
	ds_read2_b32 v[10:11], v90 offset0:49 offset1:57
	ds_read2_b32 v[12:13], v90 offset0:16 offset1:24
	ds_read2_b32 v[14:15], v90 offset0:82 offset1:90
	ds_read2_b32 v[16:17], v90 offset0:115 offset1:123
	ds_read2_b32 v[18:19], v90 offset0:148 offset1:156
	ds_read2_b32 v[20:21], v90 offset0:181 offset1:189
	ds_read2_b32 v[22:23], v90 offset0:214 offset1:222
	ds_read2_b32 v[26:27], v90 offset0:247 offset1:255
	v_lshl_add_u64 v[8:9], v[24:25], 0, v[180:181]
	global_store_dwordx4 v[8:9], v[4:7], off sc1
	v_or_b32_e32 v8, s6, v86
	v_lshlrev_b32_e32 v180, 11, v8
	s_waitcnt lgkmcnt(6)
	v_cvt_pk_bf16_f32 v4, v12, v10
	s_waitcnt lgkmcnt(4)
	v_cvt_pk_bf16_f32 v5, v14, v16
	s_waitcnt lgkmcnt(2)
	v_cvt_pk_bf16_f32 v6, v18, v20
	s_waitcnt lgkmcnt(0)
	v_cvt_pk_bf16_f32 v7, v22, v26
	v_lshl_add_u64 v[8:9], v[24:25], 0, v[180:181]
	global_store_dwordx4 v[8:9], v[4:7], off sc1
	v_or_b32_e32 v8, s6, v88
	v_lshlrev_b32_e32 v180, 11, v8
	v_cvt_pk_bf16_f32 v4, v13, v11
	v_cvt_pk_bf16_f32 v5, v15, v17
	v_cvt_pk_bf16_f32 v6, v19, v21
	v_cvt_pk_bf16_f32 v7, v23, v27
	v_lshl_add_u64 v[8:9], v[24:25], 0, v[180:181]
	global_store_dwordx4 v[8:9], v[4:7], off sc1
	s_waitcnt lgkmcnt(0)

.LBB0_789:
	v_add_u32_e32 v4, 0xc60, v28
	ds_write2_b32 v4, v18, v19 offset1:1
	v_add_u32_e32 v4, 0xc68, v28
	ds_write2_b32 v4, v16, v17 offset1:1
	v_add_u32_e32 v4, 0x1080, v28
	ds_write2_b32 v4, v12, v13 offset1:1
	v_add_u32_e32 v4, 0x1088, v28
	ds_write2_b32 v4, v14, v15 offset1:1
	s_waitcnt lgkmcnt(0)
	s_lshl_b32 s6, s27, 5
	s_lshl_b32 s7, s27, 6
	ds_read2_b32 v[8:9], v90 offset0:33 offset1:41
	ds_read2_b32 v[10:11], v90 offset1:8
	ds_read2_b32 v[12:13], v90 offset0:66 offset1:74
	ds_read2_b32 v[14:15], v90 offset0:99 offset1:107
	ds_read2_b32 v[16:17], v90 offset0:132 offset1:140
	ds_read2_b32 v[18:19], v90 offset0:165 offset1:173
	ds_read2_b32 v[20:21], v90 offset0:198 offset1:206
	ds_read2_b32 v[22:23], v90 offset0:231 offset1:239
	s_and_b32 s7, s7, 0x1f00
	s_and_b32 s6, s6, 0x60
	s_or_b32 s6, s7, s6
	s_lshl_b32 s90, s26, 1
	s_waitcnt lgkmcnt(6)
	v_cvt_pk_bf16_f32 v4, v10, v8
	v_or_b32_e32 v8, s6, v0
	v_lshl_add_u64 v[24:25], v[52:53], 0, s[90:91]
	v_lshlrev_b32_e32 v180, 11, v8
	s_waitcnt lgkmcnt(4)
	v_cvt_pk_bf16_f32 v5, v12, v14
	s_waitcnt lgkmcnt(2)
	v_cvt_pk_bf16_f32 v6, v16, v18
	s_waitcnt lgkmcnt(0)
	v_cvt_pk_bf16_f32 v7, v20, v22
	v_lshl_add_u64 v[26:27], v[24:25], 0, v[180:181]
	global_store_dwordx4 v[26:27], v[4:7], off sc1
	v_or_b32_e32 v8, s6, v85
	v_lshlrev_b32_e32 v180, 11, v8
	v_cvt_pk_bf16_f32 v4, v11, v9
	v_cvt_pk_bf16_f32 v5, v13, v15
	v_cvt_pk_bf16_f32 v6, v17, v19
	v_cvt_pk_bf16_f32 v7, v21, v23
	ds_read2_b32 v[10:11], v90 offset0:49 offset1:57
	ds_read2_b32 v[12:13], v90 offset0:16 offset1:24
	ds_read2_b32 v[14:15], v90 offset0:82 offset1:90
	ds_read2_b32 v[16:17], v90 offset0:115 offset1:123
	ds_read2_b32 v[18:19], v90 offset0:148 offset1:156
	ds_read2_b32 v[20:21], v90 offset0:181 offset1:189
	ds_read2_b32 v[22:23], v90 offset0:214 offset1:222
	ds_read2_b32 v[26:27], v90 offset0:247 offset1:255
	v_lshl_add_u64 v[8:9], v[24:25], 0, v[180:181]
	global_store_dwordx4 v[8:9], v[4:7], off sc1
	v_or_b32_e32 v8, s6, v86
	v_lshlrev_b32_e32 v180, 11, v8
	s_waitcnt lgkmcnt(6)
	v_cvt_pk_bf16_f32 v4, v12, v10
	s_waitcnt lgkmcnt(4)
	v_cvt_pk_bf16_f32 v5, v14, v16
	s_waitcnt lgkmcnt(2)
	v_cvt_pk_bf16_f32 v6, v18, v20
	s_waitcnt lgkmcnt(0)
	v_cvt_pk_bf16_f32 v7, v22, v26
	v_lshl_add_u64 v[8:9], v[24:25], 0, v[180:181]
	global_store_dwordx4 v[8:9], v[4:7], off sc1
	v_or_b32_e32 v8, s6, v88
	v_lshlrev_b32_e32 v180, 11, v8
	v_cvt_pk_bf16_f32 v4, v13, v11
	v_cvt_pk_bf16_f32 v5, v15, v17
	v_cvt_pk_bf16_f32 v6, v19, v21
	v_cvt_pk_bf16_f32 v7, v23, v27
	v_lshl_add_u64 v[8:9], v[24:25], 0, v[180:181]
	global_store_dwordx4 v[8:9], v[4:7], off sc1
	s_waitcnt lgkmcnt(0)

.LBB0_791:
	s_andn2_b64 vcc, exec, s[6:7]
	s_cbranch_vccnz .LBB0_793
	s_add_i32 s6, s49, 0x24600
	s_and_b32 s7, s6, 0x1ffc0
	s_lshl_b32 s6, s51, 5
	s_and_b32 s6, s6, 0x3e0
	v_or_b32_e32 v6, s7, v0
	s_lshl_b32 s90, s6, 2
	v_lshl_add_u64 v[4:5], v[72:73], 0, s[90:91]
	v_lshlrev_b32_e32 v180, 12, v6
	v_lshl_add_u64 v[32:33], v[4:5], 0, v[180:181]
	v_add_co_u32_e32 v8, vcc, 0x8000, v32
	global_load_dwordx4 v[4:7], v[32:33], off nt
	s_nop 0
	v_addc_co_u32_e32 v9, vcc, 0, v33, vcc
	s_mov_b32 s0, 0x10000
	global_load_dwordx4 v[8:11], v[8:9], off nt
	v_add_co_u32_e32 v12, vcc, s0, v32
	s_mov_b32 s0, 0x18000
	s_nop 0
	v_addc_co_u32_e32 v13, vcc, 0, v33, vcc
	global_load_dwordx4 v[12:15], v[12:13], off nt
	s_waitcnt vmcnt(0)
	v_add_co_u32_e32 v16, vcc, s0, v32
	v_add_u32_e32 v36, v3, v84
	s_nop 0
	v_addc_co_u32_e32 v17, vcc, 0, v33, vcc
	global_load_dwordx4 v[16:19], v[16:17], off nt
	v_add_co_u32_e32 v20, vcc, 0x20000, v32
	s_lshl_b32 s90, s7, 1
	s_nop 0
	v_addc_co_u32_e32 v21, vcc, 0, v33, vcc
	global_load_dwordx4 v[20:23], v[20:21], off nt
	v_add_co_u32_e32 v24, vcc, 0x28000, v32
	s_nop 1
	v_addc_co_u32_e32 v25, vcc, 0, v33, vcc
	global_load_dwordx4 v[24:27], v[24:25], off nt
	v_add_co_u32_e32 v28, vcc, 0x30000, v32
	s_nop 1
	v_addc_co_u32_e32 v29, vcc, 0, v33, vcc
	global_load_dwordx4 v[28:31], v[28:29], off nt
	v_add_co_u32_e32 v32, vcc, 0x38000, v32
	s_nop 1
	v_addc_co_u32_e32 v33, vcc, 0, v33, vcc
	global_load_dwordx4 v[32:35], v[32:33], off nt
	ds_write2_b32 v36, v4, v5 offset1:1
	ds_write2_b32 v36, v6, v7 offset0:2 offset1:3
	v_add_u32_e32 v4, 0x420, v36
	ds_write2_b32 v4, v8, v9 offset1:1
	v_add_u32_e32 v4, 0x428, v36
	ds_write2_b32 v4, v10, v11 offset1:1
	v_add_u32_e32 v4, 0x840, v36
	ds_write2_b32 v4, v12, v13 offset1:1
	v_add_u32_e32 v4, 0x848, v36
	ds_write2_b32 v4, v14, v15 offset1:1
	v_add_u32_e32 v4, 0xc60, v36
	s_waitcnt vmcnt(4)
	ds_write2_b32 v4, v16, v17 offset1:1
	v_add_u32_e32 v4, 0xc68, v36
	ds_write2_b32 v4, v18, v19 offset1:1
	v_add_u32_e32 v4, 0x1080, v36
	s_waitcnt vmcnt(3)
	ds_write2_b32 v4, v20, v21 offset1:1
	v_add_u32_e32 v4, 0x1088, v36
	ds_write2_b32 v4, v22, v23 offset1:1
	v_add_u32_e32 v4, 0x14a0, v36
	s_waitcnt vmcnt(2)
	ds_write2_b32 v4, v24, v25 offset1:1
	v_add_u32_e32 v4, 0x14a8, v36
	ds_write2_b32 v4, v26, v27 offset1:1
	v_add_u32_e32 v4, 0x18c0, v36
	s_waitcnt vmcnt(1)
	ds_write2_b32 v4, v28, v29 offset1:1
	v_add_u32_e32 v4, 0x18c8, v36
	ds_write2_b32 v4, v30, v31 offset1:1
	v_add_u32_e32 v4, 0x1ce0, v36
	s_waitcnt vmcnt(0)
	ds_write2_b32 v4, v32, v33 offset1:1
	v_add_u32_e32 v4, 0x1ce8, v36
	ds_write2_b32 v4, v34, v35 offset1:1
	s_waitcnt lgkmcnt(0)
	ds_read2_b32 v[10:11], v90 offset0:33 offset1:41
	ds_read2_b32 v[12:13], v90 offset1:8
	ds_read2_b32 v[14:15], v90 offset0:66 offset1:74
	ds_read2_b32 v[16:17], v90 offset0:99 offset1:107
	ds_read2_b32 v[18:19], v90 offset0:132 offset1:140
	ds_read2_b32 v[20:21], v90 offset0:165 offset1:173
	ds_read2_b32 v[22:23], v90 offset0:198 offset1:206
	ds_read2_b32 v[24:25], v90 offset0:231 offset1:239
	v_lshl_add_u64 v[4:5], v[54:55], 0, s[90:91]
	s_waitcnt lgkmcnt(6)
	v_cvt_pk_bf16_f32 v6, v12, v10
	v_or_b32_e32 v10, s6, v0
	v_mul_u32_u24_e32 v180, 0x1600, v10
	v_or_b32_e32 v10, s6, v85
	s_waitcnt lgkmcnt(4)
	v_cvt_pk_bf16_f32 v7, v14, v16
	s_waitcnt lgkmcnt(2)
	v_cvt_pk_bf16_f32 v8, v18, v20
	s_waitcnt lgkmcnt(0)
	v_cvt_pk_bf16_f32 v9, v22, v24
	v_lshl_add_u64 v[26:27], v[4:5], 0, v[180:181]
	v_mul_u32_u24_e32 v180, 0x1600, v10
	global_store_dwordx4 v[26:27], v[6:9], off sc1
	s_nop 1
	v_cvt_pk_bf16_f32 v6, v13, v11
	v_cvt_pk_bf16_f32 v7, v15, v17
	v_cvt_pk_bf16_f32 v8, v19, v21
	v_cvt_pk_bf16_f32 v9, v23, v25
	v_lshl_add_u64 v[10:11], v[4:5], 0, v[180:181]
	global_store_dwordx4 v[10:11], v[6:9], off sc1
	ds_read2_b32 v[10:11], v90 offset0:16 offset1:24
	ds_read2_b32 v[12:13], v90 offset0:49 offset1:57
	ds_read2_b32 v[14:15], v90 offset0:82 offset1:90
	ds_read2_b32 v[16:17], v90 offset0:115 offset1:123
	ds_read2_b32 v[18:19], v90 offset0:148 offset1:156
	ds_read2_b32 v[20:21], v90 offset0:181 offset1:189
	ds_read2_b32 v[22:23], v90 offset0:214 offset1:222
	ds_read2_b32 v[24:25], v90 offset0:247 offset1:255
	s_waitcnt lgkmcnt(6)
	v_cvt_pk_bf16_f32 v6, v10, v12
	v_or_b32_e32 v10, s6, v86
	v_mul_u32_u24_e32 v180, 0x1600, v10
	v_or_b32_e32 v10, s6, v88
	s_waitcnt lgkmcnt(4)
	v_cvt_pk_bf16_f32 v7, v14, v16
	s_waitcnt lgkmcnt(2)
	v_cvt_pk_bf16_f32 v8, v18, v20
	s_waitcnt lgkmcnt(0)
	v_cvt_pk_bf16_f32 v9, v22, v24
	v_lshl_add_u64 v[26:27], v[4:5], 0, v[180:181]
	v_mul_u32_u24_e32 v180, 0x1600, v10
	global_store_dwordx4 v[26:27], v[6:9], off sc1
	v_lshl_add_u64 v[4:5], v[4:5], 0, v[180:181]
	s_nop 0
	v_cvt_pk_bf16_f32 v6, v11, v13
	v_cvt_pk_bf16_f32 v7, v15, v17
	v_cvt_pk_bf16_f32 v8, v19, v21
	v_cvt_pk_bf16_f32 v9, v23, v25
	global_store_dwordx4 v[4:5], v[6:9], off sc1
	s_waitcnt lgkmcnt(0)

.LBB0_807:
	v_add_u32_e32 v4, 0xc60, v28
	ds_write2_b32 v4, v18, v19 offset1:1
	v_add_u32_e32 v4, 0xc68, v28
	ds_write2_b32 v4, v16, v17 offset1:1
	v_add_u32_e32 v4, 0x1080, v28
	ds_write2_b32 v4, v12, v13 offset1:1
	v_add_u32_e32 v4, 0x1088, v28
	ds_write2_b32 v4, v14, v15 offset1:1
	s_waitcnt lgkmcnt(0)
	s_lshl_b32 s6, s27, 5
	s_lshl_b32 s7, s27, 6
	s_and_b32 s7, s7, 0x1f00
	s_and_b32 s6, s6, 0x60
	ds_read2_b32 v[8:9], v90 offset0:33 offset1:41
	ds_read2_b32 v[10:11], v90 offset1:8
	ds_read2_b32 v[12:13], v90 offset0:66 offset1:74
	ds_read2_b32 v[14:15], v90 offset0:99 offset1:107
	ds_read2_b32 v[16:17], v90 offset0:132 offset1:140
	ds_read2_b32 v[18:19], v90 offset0:165 offset1:173
	ds_read2_b32 v[20:21], v90 offset0:198 offset1:206
	ds_read2_b32 v[22:23], v90 offset0:231 offset1:239
	s_or_b32 s6, s7, s6
	s_bitset1_b32 s6, 7
	s_lshl_b32 s90, s26, 1
	s_waitcnt lgkmcnt(6)
	v_cvt_pk_bf16_f32 v4, v10, v8
	v_or_b32_e32 v8, s6, v0
	v_lshl_add_u64 v[24:25], v[56:57], 0, s[90:91]
	v_lshlrev_b32_e32 v180, 11, v8
	s_waitcnt lgkmcnt(4)
	v_cvt_pk_bf16_f32 v5, v12, v14
	s_waitcnt lgkmcnt(2)
	v_cvt_pk_bf16_f32 v6, v16, v18
	s_waitcnt lgkmcnt(0)
	v_cvt_pk_bf16_f32 v7, v20, v22
	v_lshl_add_u64 v[26:27], v[24:25], 0, v[180:181]
	global_store_dwordx4 v[26:27], v[4:7], off sc1
	v_or_b32_e32 v8, s6, v85
	v_lshlrev_b32_e32 v180, 11, v8
	v_cvt_pk_bf16_f32 v4, v11, v9
	v_cvt_pk_bf16_f32 v5, v13, v15
	v_cvt_pk_bf16_f32 v6, v17, v19
	v_cvt_pk_bf16_f32 v7, v21, v23
	ds_read2_b32 v[10:11], v90 offset0:49 offset1:57
	ds_read2_b32 v[12:13], v90 offset0:16 offset1:24
	ds_read2_b32 v[14:15], v90 offset0:82 offset1:90
	ds_read2_b32 v[16:17], v90 offset0:115 offset1:123
	ds_read2_b32 v[18:19], v90 offset0:148 offset1:156
	ds_read2_b32 v[20:21], v90 offset0:181 offset1:189
	ds_read2_b32 v[22:23], v90 offset0:214 offset1:222
	ds_read2_b32 v[26:27], v90 offset0:247 offset1:255
	v_lshl_add_u64 v[8:9], v[24:25], 0, v[180:181]
	global_store_dwordx4 v[8:9], v[4:7], off sc1
	v_or_b32_e32 v8, s6, v86
	v_lshlrev_b32_e32 v180, 11, v8
	s_waitcnt lgkmcnt(6)
	v_cvt_pk_bf16_f32 v4, v12, v10
	s_waitcnt lgkmcnt(4)
	v_cvt_pk_bf16_f32 v5, v14, v16
	s_waitcnt lgkmcnt(2)
	v_cvt_pk_bf16_f32 v6, v18, v20
	s_waitcnt lgkmcnt(0)
	v_cvt_pk_bf16_f32 v7, v22, v26
	v_lshl_add_u64 v[8:9], v[24:25], 0, v[180:181]
	global_store_dwordx4 v[8:9], v[4:7], off sc1
	v_or_b32_e32 v8, s6, v88
	v_lshlrev_b32_e32 v180, 11, v8
	v_cvt_pk_bf16_f32 v4, v13, v11
	v_cvt_pk_bf16_f32 v5, v15, v17
	v_cvt_pk_bf16_f32 v6, v19, v21
	v_cvt_pk_bf16_f32 v7, v23, v27
	v_lshl_add_u64 v[8:9], v[24:25], 0, v[180:181]
	global_store_dwordx4 v[8:9], v[4:7], off sc1
	s_waitcnt lgkmcnt(0)
